# norm2 context rows: split-K partial sums loaded in batches (in addition to norm1 batching, S5 pass2 epilogue batching, attention VALU trims)
# speedup vs baseline: 1.0115x; 1.0055x over previous
.LBB0_2181:
	v_readlane_b32 s6, v255, 16
	v_readlane_b32 s4, v255, 10
	v_readlane_b32 s7, v255, 17
	v_readlane_b32 s5, v255, 11
	v_add_u32_e32 v128, 0xffffc000, v16
	v_ashrrev_i32_e32 v17, 31, v16
	v_cmp_gt_i32_e32 vcc, s33, v16
	v_mov_b32_e32 v2, s7
	v_mov_b32_e32 v3, s5
	v_cndmask_b32_e32 v1, 0, v17, vcc
	v_cndmask_b32_e32 v0, v128, v16, vcc
	v_cndmask_b32_e32 v3, v2, v3, vcc
	v_mov_b32_e32 v2, s6
	v_mov_b32_e32 v4, s4
	v_cndmask_b32_e32 v2, v2, v4, vcc
	v_lshlrev_b64 v[0:1], 12, v[0:1]
	v_lshl_add_u64 v[0:1], v[2:3], 0, v[0:1]
	v_mov_b32_e32 v35, v129
	v_lshl_add_u64 v[0:1], v[0:1], 0, v[34:35]
	global_load_dwordx4 v[12:15], v[0:1], off
	global_load_dwordx4 v[8:11], v[0:1], off offset:1024
	global_load_dwordx4 v[4:7], v[0:1], off offset:2048
	s_nop 0
	global_load_dwordx4 v[0:3], v[0:1], off offset:3072
	s_movk_i32 s4, 0x3fff
	v_cmp_lt_i32_e32 vcc, s4, v16
	s_and_b64 s[4:5], s[0:1], vcc
	s_and_saveexec_b64 s[42:43], s[4:5]
	s_cbranch_execz .LBB0_2180
	v_lshlrev_b64 v[42:43], 12, v[128:129]
	v_lshl_add_u64 v[50:51], v[28:29], 0, v[42:43]
	global_load_dwordx4 v[42:45], v[50:51], off
	v_add_co_u32_e32 v48, vcc, 0x200000, v50
	v_lshlrev_b64 v[62:63], 12, v[16:17]
	s_nop 0
	v_addc_co_u32_e32 v49, vcc, 0, v51, vcc
	s_waitcnt vmcnt(0) lgkmcnt(0)
	v_pk_add_f32 v[46:47], v[44:45], 0 op_sel_hi:[1,0]
	v_pk_add_f32 v[58:59], v[42:43], 0 op_sel_hi:[1,0]
	global_load_dwordx4 v[42:45], v[48:49], off
	s_waitcnt vmcnt(0) lgkmcnt(0)
	v_pk_add_f32 v[60:61], v[46:47], v[44:45]
	v_add_co_u32_e32 v46, vcc, 0x400000, v50
	v_pk_add_f32 v[58:59], v[58:59], v[42:43]
	s_nop 0
	v_addc_co_u32_e32 v47, vcc, 0, v51, vcc
	global_load_dwordx4 v[42:45], v[46:47], off
	s_waitcnt vmcnt(0) lgkmcnt(0)
	v_pk_add_f32 v[64:65], v[60:61], v[44:45]
	v_add_co_u32_e32 v44, vcc, 0x600000, v50
	v_pk_add_f32 v[42:43], v[58:59], v[42:43]
	s_nop 0
	v_addc_co_u32_e32 v45, vcc, 0, v51, vcc
	global_load_dwordx4 v[58:61], v[44:45], off
	s_waitcnt vmcnt(0) lgkmcnt(0)
	v_pk_add_f32 v[64:65], v[64:65], v[60:61]
	v_pk_add_f32 v[42:43], v[42:43], v[58:59]
	global_load_dwordx4 v[58:61], v[20:21], off
	s_waitcnt vmcnt(0) lgkmcnt(0)
	v_pk_fma_f32 v[14:15], v[64:65], v[60:61], v[14:15]
	v_pk_fma_f32 v[12:13], v[42:43], v[58:59], v[12:13]
	global_load_dwordx4 v[84:87], v[50:51], off offset:1024
	global_load_dwordx4 v[88:91], v[48:49], off offset:1024
	global_load_dwordx4 v[92:95], v[46:47], off offset:1024
	global_load_dwordx4 v[96:99], v[44:45], off offset:1024
	global_load_dwordx4 v[100:103], v[22:23], off
	s_waitcnt vmcnt(0)
	v_lshl_add_u64 v[42:43], v[30:31], 0, v[62:63]
	global_store_dwordx4 v[42:43], v[12:15], off
	v_pk_add_f32 v[62:63], v[86:87], 0 op_sel_hi:[1,0]
	v_pk_add_f32 v[64:65], v[84:85], 0 op_sel_hi:[1,0]
	v_pk_add_f32 v[62:63], v[62:63], v[90:91]
	v_pk_add_f32 v[64:65], v[64:65], v[88:89]
	v_pk_add_f32 v[62:63], v[62:63], v[94:95]
	v_pk_add_f32 v[64:65], v[64:65], v[92:93]
	v_pk_add_f32 v[62:63], v[62:63], v[98:99]
	v_pk_add_f32 v[64:65], v[64:65], v[96:97]
	v_pk_fma_f32 v[10:11], v[62:63], v[102:103], v[10:11]
	v_pk_fma_f32 v[8:9], v[64:65], v[100:101], v[8:9]
	global_load_dwordx4 v[84:87], v[50:51], off offset:2048
	global_load_dwordx4 v[88:91], v[48:49], off offset:2048
	global_load_dwordx4 v[92:95], v[46:47], off offset:2048
	global_load_dwordx4 v[96:99], v[44:45], off offset:2048
	global_load_dwordx4 v[100:103], v[24:25], off
	s_waitcnt vmcnt(0)
	v_pk_add_f32 v[62:63], v[86:87], 0 op_sel_hi:[1,0]
	v_pk_add_f32 v[64:65], v[84:85], 0 op_sel_hi:[1,0]
	v_pk_add_f32 v[62:63], v[62:63], v[90:91]
	v_pk_add_f32 v[64:65], v[64:65], v[88:89]
	v_pk_add_f32 v[62:63], v[62:63], v[94:95]
	v_pk_add_f32 v[64:65], v[64:65], v[92:93]
	v_pk_add_f32 v[62:63], v[62:63], v[98:99]
	v_pk_add_f32 v[64:65], v[64:65], v[96:97]
	v_pk_fma_f32 v[6:7], v[62:63], v[102:103], v[6:7]
	v_pk_fma_f32 v[4:5], v[64:65], v[100:101], v[4:5]
	global_load_dwordx4 v[84:87], v[50:51], off offset:3072
	global_load_dwordx4 v[88:91], v[48:49], off offset:3072
	global_load_dwordx4 v[92:95], v[46:47], off offset:3072
	global_load_dwordx4 v[96:99], v[44:45], off offset:3072
	global_load_dwordx4 v[100:103], v[26:27], off
	s_waitcnt vmcnt(0)
	v_pk_add_f32 v[58:59], v[84:85], 0 op_sel_hi:[1,0]
	v_pk_add_f32 v[60:61], v[86:87], 0 op_sel_hi:[1,0]
	global_store_dwordx4 v[42:43], v[8:11], off offset:1024
	global_store_dwordx4 v[42:43], v[4:7], off offset:2048
	v_pk_add_f32 v[58:59], v[58:59], v[88:89]
	v_pk_add_f32 v[50:51], v[60:61], v[90:91]
	v_pk_add_f32 v[48:49], v[50:51], v[94:95]
	v_pk_add_f32 v[50:51], v[58:59], v[92:93]
	v_pk_add_f32 v[48:49], v[48:49], v[98:99]
	v_pk_add_f32 v[50:51], v[50:51], v[96:97]
	v_pk_fma_f32 v[2:3], v[48:49], v[102:103], v[2:3]
	v_pk_fma_f32 v[0:1], v[50:51], v[100:101], v[0:1]
	global_store_dwordx4 v[42:43], v[0:3], off offset:3072
	s_branch .LBB0_2180
